# speedup vs baseline: 1.0169x; 1.0001x over previous
; __device__ __forceinline__ void phase_gemm_res(const Params& p, int L, const u16* A, int K, const u16* Bt, int gidx, float factor, char* lds) {
;     ...
;       const int rlo = m0 + wm * 96, rhi = rlo + 95;
;       const int clo = rlo < TL ? (rlo >> 13) : 4;
;       float g0[4], g1[4];
;       { const float* ga_ = modp(p, L, rlo, gidx) + n0 + wn * 64 + l15; const float* gb_ = modp(p, L, rhi, gidx) + n0 + wn * 64 + l15;
; #pragma unroll
;         for (int ni = 0; ni < 4; ++ni) { g0[ni] = ga_[ni * 16]; g1[ni] = gb_[ni * 16]; } }
; #pragma unroll
;       for (int mp = 0; mp < 3; ++mp) {
;         float xv[2][4][4];
; #pragma unroll
;         for (int u = 0; u < 2; ++u)
; #pragma unroll
;           for (int j = 0; j < 4; ++j) {
;             const float* xr = xrow(p, m0 + wm * 96 + (2 * mp + u) * 16 + quad * 4 + j) + n0 + wn * 64 + l15;
; #pragma unroll
;             for (int ni = 0; ni < 4; ++ni) xv[u][j][ni] = xr[ni * 16];
.LBB0_1757:
	s_ashr_i32 s4, s63, 31
	s_lshr_b32 s5, s4, 28
	s_lshr_b32 s4, s4, 30
	s_add_i32 s5, s63, s5
	s_add_i32 s4, s63, s4
	s_lshr_b32 s75, s5, 2
	s_and_b32 s4, s4, 0x3fffffc
	s_and_b32 s75, s75, 0x3fffffc
	s_sub_i32 s4, s63, s4
	s_add_i32 s4, s75, s4
	s_mul_i32 s75, s4, 0xc0
	s_and_b32 s4, s5, 0xfff0
	s_sub_i32 s4, s63, s4
	s_bfe_i32 s5, s4, 0x80000
	s_bfe_u32 s5, s5, 0x2000d
	v_mov_b32 v126, v200
	v_mov_b32 v106, v200
	s_add_i32 s4, s4, s5
	v_lshrrev_b32_e32 v107, 8, v106
	v_and_b32_e32 v115, 0xc0, v106
	v_mov_b32_e32 v106, s75
	s_movk_i32 s5, 0x60
	v_mad_i32_i24 v127, v107, s5, v106
	v_min_i32_e32 v114, 0x8000, v127
	v_ashrrev_i32_e32 v106, 13, v114
	s_bfe_i32 s4, s4, 0x80000
	v_add_u32_e32 v106, s53, v106
	s_sext_i32_i16 s4, s4
	v_lshl_add_u32 v106, v106, 3, v106
	s_lshl_b32 s4, s4, 6
	v_ashrrev_i32_e32 v107, 31, v106
	s_and_b32 s4, s4, 0xffffff00
	v_lshl_add_u64 v[106:107], s[0:1], 0, v[106:107]
	v_readlane_b32 s12, v254, 7
	v_lshlrev_b64 v[106:107], 12, v[106:107]
	v_readlane_b32 s13, v254, 8
	s_ashr_i32 s5, s4, 31
	v_lshlrev_b32_e32 v128, 2, v115
	v_min_i32_e32 v115, 0x7fa1, v127
	v_lshl_add_u64 v[106:107], s[12:13], 0, v[106:107]
	s_lshl_b64 s[4:5], s[4:5], 2
	v_add_u32_e32 v115, 0x5f, v115
	v_and_b32_e32 v118, 15, v126
	v_lshl_add_u64 v[106:107], v[106:107], 0, s[4:5]
	v_ashrrev_i32_e32 v115, 13, v115
	v_lshl_add_u64 v[116:117], v[106:107], 0, v[128:129]
	v_lshlrev_b32_e32 v106, 2, v118
	v_mov_b32_e32 v107, v129
	v_add_u32_e32 v115, s53, v115
	v_lshl_add_u64 v[122:123], v[116:117], 0, v[106:107]
	v_lshl_add_u32 v116, v115, 3, v115
	v_ashrrev_i32_e32 v117, 31, v116
	v_lshl_add_u64 v[116:117], s[0:1], 0, v[116:117]
	v_lshlrev_b64 v[116:117], 12, v[116:117]
	v_lshl_add_u64 v[116:117], s[12:13], 0, v[116:117]
	v_lshl_add_u64 v[116:117], v[116:117], 0, s[4:5]
	v_lshl_add_u64 v[116:117], v[116:117], 0, v[128:129]
	v_lshl_add_u64 v[124:125], v[116:117], 0, v[106:107]
	global_load_dword v115, v[122:123], off
	global_load_dword v116, v[124:125], off
	global_load_dword v117, v[122:123], off offset:64
	global_load_dword v118, v[124:125], off offset:64
	global_load_dword v119, v[122:123], off offset:128
	global_load_dword v120, v[124:125], off offset:128
	global_load_dword v121, v[124:125], off offset:192
	s_nop 0
	global_load_dword v122, v[122:123], off offset:192
	v_lshrrev_b32_e32 v123, 2, v126
	v_readlane_b32 s26, v253, 46
	v_readlane_b32 s27, v253, 47
	v_and_or_b32 v123, v123, 12, v127
	v_lshl_add_u64 v[182:183], v[106:107], 0, s[4:5]
	v_lshl_add_u64 v[182:183], v[182:183], 0, v[128:129]
	v_mov_b32_e32 v185, 0x1000
	v_lshl_add_u64 v[186:187], v[182:183], 0, s[26:27]
	v_lshl_add_u64 v[188:189], v[182:183], 0, s[58:59]
	v_mov_b32_e32 v180, v123
	v_cmp_gt_i32_e32 vcc, s77, v180
	v_add_u32_e32 v181, 0xffff8000, v123
	s_nop 1
	v_cndmask_b32_e32 v132, v181, v180, vcc
	v_cndmask_b32_e32 v182, v188, v186, vcc
	v_cndmask_b32_e32 v183, v189, v187, vcc
	v_mad_u64_u32 v[132:133], vcc, v132, v185, v[182:183]
	global_load_dword v140, v[132:133], off
	global_load_dword v141, v[132:133], off offset:64
	global_load_dword v142, v[132:133], off offset:128
	global_load_dword v143, v[132:133], off offset:192
	v_add_u32_e32 v180, 0x1, v123
	v_cmp_gt_i32_e32 vcc, s77, v180
	v_add_u32_e32 v181, 0xffff8001, v123
	s_nop 1
	v_cndmask_b32_e32 v134, v181, v180, vcc
	v_cndmask_b32_e32 v182, v188, v186, vcc
	v_cndmask_b32_e32 v183, v189, v187, vcc
	v_mad_u64_u32 v[134:135], vcc, v134, v185, v[182:183]
	global_load_dword v144, v[134:135], off
	global_load_dword v145, v[134:135], off offset:64
	global_load_dword v146, v[134:135], off offset:128
	global_load_dword v147, v[134:135], off offset:192
	v_add_u32_e32 v180, 0x2, v123
	v_cmp_gt_i32_e32 vcc, s77, v180
	v_add_u32_e32 v181, 0xffff8002, v123
	s_nop 1
	v_cndmask_b32_e32 v136, v181, v180, vcc
	v_cndmask_b32_e32 v182, v188, v186, vcc
	v_cndmask_b32_e32 v183, v189, v187, vcc
	v_mad_u64_u32 v[136:137], vcc, v136, v185, v[182:183]
	global_load_dword v148, v[136:137], off
	global_load_dword v149, v[136:137], off offset:64
	global_load_dword v150, v[136:137], off offset:128
	global_load_dword v151, v[136:137], off offset:192
	v_add_u32_e32 v180, 0x3, v123
	v_cmp_gt_i32_e32 vcc, s77, v180
	v_add_u32_e32 v181, 0xffff8003, v123
	s_nop 1
	v_cndmask_b32_e32 v138, v181, v180, vcc
	v_cndmask_b32_e32 v182, v188, v186, vcc
	v_cndmask_b32_e32 v183, v189, v187, vcc
	v_mad_u64_u32 v[138:139], vcc, v138, v185, v[182:183]
	global_load_dword v152, v[138:139], off
	global_load_dword v153, v[138:139], off offset:64
	global_load_dword v154, v[138:139], off offset:128
	global_load_dword v155, v[138:139], off offset:192
	v_add_u32_e32 v180, 0x10, v123
	v_cmp_gt_i32_e32 vcc, s77, v180
	v_add_u32_e32 v181, 0xffff8010, v123
	s_nop 1
	v_cndmask_b32_e32 v156, v181, v180, vcc
	v_cndmask_b32_e32 v182, v188, v186, vcc
	v_cndmask_b32_e32 v183, v189, v187, vcc
	v_mad_u64_u32 v[156:157], vcc, v156, v185, v[182:183]
	global_load_dword v164, v[156:157], off
	global_load_dword v165, v[156:157], off offset:64
	global_load_dword v166, v[156:157], off offset:128
	global_load_dword v167, v[156:157], off offset:192
	v_add_u32_e32 v180, 0x11, v123
	v_cmp_gt_i32_e32 vcc, s77, v180
	v_add_u32_e32 v181, 0xffff8011, v123
	s_nop 1
	v_cndmask_b32_e32 v158, v181, v180, vcc
	v_cndmask_b32_e32 v182, v188, v186, vcc
	v_cndmask_b32_e32 v183, v189, v187, vcc
	v_mad_u64_u32 v[158:159], vcc, v158, v185, v[182:183]
	global_load_dword v168, v[158:159], off
	global_load_dword v169, v[158:159], off offset:64
	global_load_dword v170, v[158:159], off offset:128
	global_load_dword v171, v[158:159], off offset:192
	v_add_u32_e32 v180, 0x12, v123
	v_cmp_gt_i32_e32 vcc, s77, v180
	v_add_u32_e32 v181, 0xffff8012, v123
	s_nop 1
	v_cndmask_b32_e32 v160, v181, v180, vcc
	v_cndmask_b32_e32 v182, v188, v186, vcc
	v_cndmask_b32_e32 v183, v189, v187, vcc
	v_mad_u64_u32 v[160:161], vcc, v160, v185, v[182:183]
	global_load_dword v172, v[160:161], off
	global_load_dword v173, v[160:161], off offset:64
	global_load_dword v174, v[160:161], off offset:128
	global_load_dword v175, v[160:161], off offset:192
	v_add_u32_e32 v180, 0x13, v123
	v_cmp_gt_i32_e32 vcc, s77, v180
	v_add_u32_e32 v181, 0xffff8013, v123
	s_nop 1
	v_cndmask_b32_e32 v162, v181, v180, vcc
	v_cndmask_b32_e32 v182, v188, v186, vcc
	v_cndmask_b32_e32 v183, v189, v187, vcc
	v_mad_u64_u32 v[162:163], vcc, v162, v185, v[182:183]
	global_load_dword v176, v[162:163], off
	global_load_dword v177, v[162:163], off offset:64
	global_load_dword v178, v[162:163], off offset:128
	global_load_dword v179, v[162:163], off offset:192
	s_waitcnt vmcnt(16)
; __device__ __forceinline__ void phase_gemm_res(const Params& p, int L, const u16* A, int K, const u16* Bt, int gidx, float factor, char* lds) {
;     ...
; #pragma unroll
;           for (int j = 0; j < 4; ++j) {
;             const int row = m0 + wm * 96 + (2 * mp + u) * 16 + quad * 4 + j;
;             float* xr = xrow(p, row) + n0 + wn * 64 + l15;
;             const bool lo = (row < TL ? (row >> 13) : 4) == clo;
;             float gv[4];
; #pragma unroll
;             for (int ni = 0; ni < 4; ++ni) gv[ni] = lo ? g0[ni] : g1[ni];
; #pragma unroll
;             for (int ni = 0; ni < 4; ++ni) xr[ni * 16] = xv[u][j][ni] + factor * gv[ni] * acc[2 * mp + u][ni][j];
	v_mov_b32_e32 v180, v123
	v_min_i32_e32 v180, 0x8000, v180
	v_xor_b32_e32 v180, v180, v114
	v_cmp_gt_u32_e32 vcc, s10, v180
	s_nop 1
	v_cndmask_b32_e32 v181, v116, v115, vcc
	v_cndmask_b32_e32 v182, v118, v117, vcc
	v_cndmask_b32_e32 v183, v120, v119, vcc
	v_cndmask_b32_e32 v184, v121, v122, vcc
	v_mul_f32_e32 v181, s8, v181
	v_mul_f32_e32 v182, s8, v182
	v_mul_f32_e32 v183, s8, v183
	v_mul_f32_e32 v184, s8, v184
	v_fmac_f32_e32 v140, v92, v181
	v_fmac_f32_e32 v141, v88, v182
	v_fmac_f32_e32 v142, v84, v183
	v_fmac_f32_e32 v143, v80, v184
	global_store_dword v[132:133], v140, off
	global_store_dword v[132:133], v141, off offset:64
	global_store_dword v[132:133], v142, off offset:128
	global_store_dword v[132:133], v143, off offset:192
	v_add_u32_e32 v180, 0x1, v123
	v_min_i32_e32 v180, 0x8000, v180
	v_xor_b32_e32 v180, v180, v114
	v_cmp_gt_u32_e32 vcc, s10, v180
	s_nop 1
	v_cndmask_b32_e32 v181, v116, v115, vcc
	v_cndmask_b32_e32 v182, v118, v117, vcc
	v_cndmask_b32_e32 v183, v120, v119, vcc
	v_cndmask_b32_e32 v184, v121, v122, vcc
	v_mul_f32_e32 v181, s8, v181
	v_mul_f32_e32 v182, s8, v182
	v_mul_f32_e32 v183, s8, v183
	v_mul_f32_e32 v184, s8, v184
	v_fmac_f32_e32 v144, v93, v181
	v_fmac_f32_e32 v145, v89, v182
	v_fmac_f32_e32 v146, v85, v183
	v_fmac_f32_e32 v147, v81, v184
	global_store_dword v[134:135], v144, off
	global_store_dword v[134:135], v145, off offset:64
	global_store_dword v[134:135], v146, off offset:128
	global_store_dword v[134:135], v147, off offset:192
	v_add_u32_e32 v180, 0x2, v123
	v_min_i32_e32 v180, 0x8000, v180
	v_xor_b32_e32 v180, v180, v114
	v_cmp_gt_u32_e32 vcc, s10, v180
	s_nop 1
	v_cndmask_b32_e32 v181, v116, v115, vcc
	v_cndmask_b32_e32 v182, v118, v117, vcc
	v_cndmask_b32_e32 v183, v120, v119, vcc
	v_cndmask_b32_e32 v184, v121, v122, vcc
	v_mul_f32_e32 v181, s8, v181
	v_mul_f32_e32 v182, s8, v182
	v_mul_f32_e32 v183, s8, v183
	v_mul_f32_e32 v184, s8, v184
	v_fmac_f32_e32 v148, v94, v181
	v_fmac_f32_e32 v149, v90, v182
	v_fmac_f32_e32 v150, v86, v183
	v_fmac_f32_e32 v151, v82, v184
	global_store_dword v[136:137], v148, off
	global_store_dword v[136:137], v149, off offset:64
	global_store_dword v[136:137], v150, off offset:128
	global_store_dword v[136:137], v151, off offset:192
	v_add_u32_e32 v180, 0x3, v123
	v_min_i32_e32 v180, 0x8000, v180
	v_xor_b32_e32 v180, v180, v114
	v_cmp_gt_u32_e32 vcc, s10, v180
	s_nop 1
	v_cndmask_b32_e32 v181, v116, v115, vcc
	v_cndmask_b32_e32 v182, v118, v117, vcc
	v_cndmask_b32_e32 v183, v120, v119, vcc
	v_cndmask_b32_e32 v184, v121, v122, vcc
	v_mul_f32_e32 v181, s8, v181
	v_mul_f32_e32 v182, s8, v182
	v_mul_f32_e32 v183, s8, v183
	v_mul_f32_e32 v184, s8, v184
	v_fmac_f32_e32 v152, v95, v181
	v_fmac_f32_e32 v153, v91, v182
	v_fmac_f32_e32 v154, v87, v183
	v_fmac_f32_e32 v155, v83, v184
	global_store_dword v[138:139], v152, off
	global_store_dword v[138:139], v153, off offset:64
	global_store_dword v[138:139], v154, off offset:128
	global_store_dword v[138:139], v155, off offset:192
	v_add_u32_e32 v180, 0x20, v123
	v_cmp_gt_i32_e32 vcc, s77, v180
	v_add_u32_e32 v181, 0xffff8020, v123
	s_nop 1
	v_cndmask_b32_e32 v132, v181, v180, vcc
	v_cndmask_b32_e32 v182, v188, v186, vcc
	v_cndmask_b32_e32 v183, v189, v187, vcc
	v_mad_u64_u32 v[132:133], vcc, v132, v185, v[182:183]
	global_load_dword v140, v[132:133], off
	global_load_dword v141, v[132:133], off offset:64
	global_load_dword v142, v[132:133], off offset:128
	global_load_dword v143, v[132:133], off offset:192
	v_add_u32_e32 v180, 0x21, v123
	v_cmp_gt_i32_e32 vcc, s77, v180
	v_add_u32_e32 v181, 0xffff8021, v123
	s_nop 1
	v_cndmask_b32_e32 v134, v181, v180, vcc
	v_cndmask_b32_e32 v182, v188, v186, vcc
	v_cndmask_b32_e32 v183, v189, v187, vcc
	v_mad_u64_u32 v[134:135], vcc, v134, v185, v[182:183]
	global_load_dword v144, v[134:135], off
	global_load_dword v145, v[134:135], off offset:64
	global_load_dword v146, v[134:135], off offset:128
	global_load_dword v147, v[134:135], off offset:192
	v_add_u32_e32 v180, 0x22, v123
	v_cmp_gt_i32_e32 vcc, s77, v180
	v_add_u32_e32 v181, 0xffff8022, v123
	s_nop 1
	v_cndmask_b32_e32 v136, v181, v180, vcc
	v_cndmask_b32_e32 v182, v188, v186, vcc
	v_cndmask_b32_e32 v183, v189, v187, vcc
	v_mad_u64_u32 v[136:137], vcc, v136, v185, v[182:183]
	global_load_dword v148, v[136:137], off
	global_load_dword v149, v[136:137], off offset:64
	global_load_dword v150, v[136:137], off offset:128
	global_load_dword v151, v[136:137], off offset:192
	v_add_u32_e32 v180, 0x23, v123
	v_cmp_gt_i32_e32 vcc, s77, v180
	v_add_u32_e32 v181, 0xffff8023, v123
	s_nop 1
	v_cndmask_b32_e32 v138, v181, v180, vcc
	v_cndmask_b32_e32 v182, v188, v186, vcc
	v_cndmask_b32_e32 v183, v189, v187, vcc
	v_mad_u64_u32 v[138:139], vcc, v138, v185, v[182:183]
	global_load_dword v152, v[138:139], off
	global_load_dword v153, v[138:139], off offset:64
	global_load_dword v154, v[138:139], off offset:128
	global_load_dword v155, v[138:139], off offset:192
	s_waitcnt vmcnt(31)
; __device__ __forceinline__ void phase_gemm_res(const Params& p, int L, const u16* A, int K, const u16* Bt, int gidx, float factor, char* lds) {
;     ...
; #pragma unroll
;           for (int j = 0; j < 4; ++j) {
;             const int row = m0 + wm * 96 + (2 * mp + u) * 16 + quad * 4 + j;
;             float* xr = xrow(p, row) + n0 + wn * 64 + l15;
;             const bool lo = (row < TL ? (row >> 13) : 4) == clo;
;             float gv[4];
; #pragma unroll
;             for (int ni = 0; ni < 4; ++ni) gv[ni] = lo ? g0[ni] : g1[ni];
; #pragma unroll
;             for (int ni = 0; ni < 4; ++ni) xr[ni * 16] = xv[u][j][ni] + factor * gv[ni] * acc[2 * mp + u][ni][j];
	v_add_u32_e32 v180, 0x10, v123
	v_min_i32_e32 v180, 0x8000, v180
	v_xor_b32_e32 v180, v180, v114
	v_cmp_gt_u32_e32 vcc, s10, v180
	s_nop 1
	v_cndmask_b32_e32 v181, v116, v115, vcc
	v_cndmask_b32_e32 v182, v118, v117, vcc
	v_cndmask_b32_e32 v183, v120, v119, vcc
	v_cndmask_b32_e32 v184, v121, v122, vcc
	v_mul_f32_e32 v181, s8, v181
	v_mul_f32_e32 v182, s8, v182
	v_mul_f32_e32 v183, s8, v183
	v_mul_f32_e32 v184, s8, v184
	v_fmac_f32_e32 v164, v76, v181
	v_fmac_f32_e32 v165, v72, v182
	v_fmac_f32_e32 v166, v68, v183
	v_fmac_f32_e32 v167, v64, v184
	global_store_dword v[156:157], v164, off
	global_store_dword v[156:157], v165, off offset:64
	global_store_dword v[156:157], v166, off offset:128
	global_store_dword v[156:157], v167, off offset:192
	v_add_u32_e32 v180, 0x11, v123
	v_min_i32_e32 v180, 0x8000, v180
	v_xor_b32_e32 v180, v180, v114
	v_cmp_gt_u32_e32 vcc, s10, v180
	s_nop 1
	v_cndmask_b32_e32 v181, v116, v115, vcc
	v_cndmask_b32_e32 v182, v118, v117, vcc
	v_cndmask_b32_e32 v183, v120, v119, vcc
	v_cndmask_b32_e32 v184, v121, v122, vcc
	v_mul_f32_e32 v181, s8, v181
	v_mul_f32_e32 v182, s8, v182
	v_mul_f32_e32 v183, s8, v183
	v_mul_f32_e32 v184, s8, v184
	v_fmac_f32_e32 v168, v77, v181
	v_fmac_f32_e32 v169, v73, v182
	v_fmac_f32_e32 v170, v69, v183
	v_fmac_f32_e32 v171, v65, v184
	global_store_dword v[158:159], v168, off
	global_store_dword v[158:159], v169, off offset:64
	global_store_dword v[158:159], v170, off offset:128
	global_store_dword v[158:159], v171, off offset:192
	v_add_u32_e32 v180, 0x12, v123
	v_min_i32_e32 v180, 0x8000, v180
	v_xor_b32_e32 v180, v180, v114
	v_cmp_gt_u32_e32 vcc, s10, v180
	s_nop 1
	v_cndmask_b32_e32 v181, v116, v115, vcc
	v_cndmask_b32_e32 v182, v118, v117, vcc
	v_cndmask_b32_e32 v183, v120, v119, vcc
	v_cndmask_b32_e32 v184, v121, v122, vcc
	v_mul_f32_e32 v181, s8, v181
	v_mul_f32_e32 v182, s8, v182
	v_mul_f32_e32 v183, s8, v183
	v_mul_f32_e32 v184, s8, v184
	v_fmac_f32_e32 v172, v78, v181
	v_fmac_f32_e32 v173, v74, v182
	v_fmac_f32_e32 v174, v70, v183
	v_fmac_f32_e32 v175, v66, v184
	global_store_dword v[160:161], v172, off
	global_store_dword v[160:161], v173, off offset:64
	global_store_dword v[160:161], v174, off offset:128
	global_store_dword v[160:161], v175, off offset:192
	v_add_u32_e32 v180, 0x13, v123
	v_min_i32_e32 v180, 0x8000, v180
	v_xor_b32_e32 v180, v180, v114
	v_cmp_gt_u32_e32 vcc, s10, v180
	s_nop 1
	v_cndmask_b32_e32 v181, v116, v115, vcc
	v_cndmask_b32_e32 v182, v118, v117, vcc
	v_cndmask_b32_e32 v183, v120, v119, vcc
	v_cndmask_b32_e32 v184, v121, v122, vcc
	v_mul_f32_e32 v181, s8, v181
	v_mul_f32_e32 v182, s8, v182
	v_mul_f32_e32 v183, s8, v183
	v_mul_f32_e32 v184, s8, v184
	v_fmac_f32_e32 v176, v79, v181
	v_fmac_f32_e32 v177, v75, v182
	v_fmac_f32_e32 v178, v71, v183
	v_fmac_f32_e32 v179, v67, v184
	global_store_dword v[162:163], v176, off
	global_store_dword v[162:163], v177, off offset:64
	global_store_dword v[162:163], v178, off offset:128
	global_store_dword v[162:163], v179, off offset:192
	v_add_u32_e32 v180, 0x30, v123
	v_cmp_gt_i32_e32 vcc, s77, v180
	v_add_u32_e32 v181, 0xffff8030, v123
	s_nop 1
	v_cndmask_b32_e32 v156, v181, v180, vcc
	v_cndmask_b32_e32 v182, v188, v186, vcc
	v_cndmask_b32_e32 v183, v189, v187, vcc
	v_mad_u64_u32 v[156:157], vcc, v156, v185, v[182:183]
	global_load_dword v164, v[156:157], off
	global_load_dword v165, v[156:157], off offset:64
	global_load_dword v166, v[156:157], off offset:128
	global_load_dword v167, v[156:157], off offset:192
	v_add_u32_e32 v180, 0x31, v123
	v_cmp_gt_i32_e32 vcc, s77, v180
	v_add_u32_e32 v181, 0xffff8031, v123
	s_nop 1
	v_cndmask_b32_e32 v158, v181, v180, vcc
	v_cndmask_b32_e32 v182, v188, v186, vcc
	v_cndmask_b32_e32 v183, v189, v187, vcc
	v_mad_u64_u32 v[158:159], vcc, v158, v185, v[182:183]
	global_load_dword v168, v[158:159], off
	global_load_dword v169, v[158:159], off offset:64
	global_load_dword v170, v[158:159], off offset:128
	global_load_dword v171, v[158:159], off offset:192
	v_add_u32_e32 v180, 0x32, v123
	v_cmp_gt_i32_e32 vcc, s77, v180
	v_add_u32_e32 v181, 0xffff8032, v123
	s_nop 1
	v_cndmask_b32_e32 v160, v181, v180, vcc
	v_cndmask_b32_e32 v182, v188, v186, vcc
	v_cndmask_b32_e32 v183, v189, v187, vcc
	v_mad_u64_u32 v[160:161], vcc, v160, v185, v[182:183]
	global_load_dword v172, v[160:161], off
	global_load_dword v173, v[160:161], off offset:64
	global_load_dword v174, v[160:161], off offset:128
	global_load_dword v175, v[160:161], off offset:192
	v_add_u32_e32 v180, 0x33, v123
	v_cmp_gt_i32_e32 vcc, s77, v180
	v_add_u32_e32 v181, 0xffff8033, v123
	s_nop 1
	v_cndmask_b32_e32 v162, v181, v180, vcc
	v_cndmask_b32_e32 v182, v188, v186, vcc
	v_cndmask_b32_e32 v183, v189, v187, vcc
	v_mad_u64_u32 v[162:163], vcc, v162, v185, v[182:183]
	global_load_dword v176, v[162:163], off
	global_load_dword v177, v[162:163], off offset:64
	global_load_dword v178, v[162:163], off offset:128
	global_load_dword v179, v[162:163], off offset:192
	s_waitcnt vmcnt(31)
; __device__ __forceinline__ void phase_gemm_res(const Params& p, int L, const u16* A, int K, const u16* Bt, int gidx, float factor, char* lds) {
;     ...
; #pragma unroll
;           for (int j = 0; j < 4; ++j) {
;             const int row = m0 + wm * 96 + (2 * mp + u) * 16 + quad * 4 + j;
;             float* xr = xrow(p, row) + n0 + wn * 64 + l15;
;             const bool lo = (row < TL ? (row >> 13) : 4) == clo;
;             float gv[4];
; #pragma unroll
;             for (int ni = 0; ni < 4; ++ni) gv[ni] = lo ? g0[ni] : g1[ni];
; #pragma unroll
;             for (int ni = 0; ni < 4; ++ni) xr[ni * 16] = xv[u][j][ni] + factor * gv[ni] * acc[2 * mp + u][ni][j];
	v_add_u32_e32 v180, 0x20, v123
	v_min_i32_e32 v180, 0x8000, v180
	v_xor_b32_e32 v180, v180, v114
	v_cmp_gt_u32_e32 vcc, s10, v180
	s_nop 1
	v_cndmask_b32_e32 v181, v116, v115, vcc
	v_cndmask_b32_e32 v182, v118, v117, vcc
	v_cndmask_b32_e32 v183, v120, v119, vcc
	v_cndmask_b32_e32 v184, v121, v122, vcc
	v_mul_f32_e32 v181, s8, v181
	v_mul_f32_e32 v182, s8, v182
	v_mul_f32_e32 v183, s8, v183
	v_mul_f32_e32 v184, s8, v184
	v_fmac_f32_e32 v140, v60, v181
	v_fmac_f32_e32 v141, v56, v182
	v_fmac_f32_e32 v142, v52, v183
	v_fmac_f32_e32 v143, v48, v184
	global_store_dword v[132:133], v140, off
	global_store_dword v[132:133], v141, off offset:64
	global_store_dword v[132:133], v142, off offset:128
	global_store_dword v[132:133], v143, off offset:192
	v_add_u32_e32 v180, 0x21, v123
	v_min_i32_e32 v180, 0x8000, v180
	v_xor_b32_e32 v180, v180, v114
	v_cmp_gt_u32_e32 vcc, s10, v180
	s_nop 1
	v_cndmask_b32_e32 v181, v116, v115, vcc
	v_cndmask_b32_e32 v182, v118, v117, vcc
	v_cndmask_b32_e32 v183, v120, v119, vcc
	v_cndmask_b32_e32 v184, v121, v122, vcc
	v_mul_f32_e32 v181, s8, v181
	v_mul_f32_e32 v182, s8, v182
	v_mul_f32_e32 v183, s8, v183
	v_mul_f32_e32 v184, s8, v184
	v_fmac_f32_e32 v144, v61, v181
	v_fmac_f32_e32 v145, v57, v182
	v_fmac_f32_e32 v146, v53, v183
	v_fmac_f32_e32 v147, v49, v184
	global_store_dword v[134:135], v144, off
	global_store_dword v[134:135], v145, off offset:64
	global_store_dword v[134:135], v146, off offset:128
	global_store_dword v[134:135], v147, off offset:192
	v_add_u32_e32 v180, 0x22, v123
	v_min_i32_e32 v180, 0x8000, v180
	v_xor_b32_e32 v180, v180, v114
	v_cmp_gt_u32_e32 vcc, s10, v180
	s_nop 1
	v_cndmask_b32_e32 v181, v116, v115, vcc
	v_cndmask_b32_e32 v182, v118, v117, vcc
	v_cndmask_b32_e32 v183, v120, v119, vcc
	v_cndmask_b32_e32 v184, v121, v122, vcc
	v_mul_f32_e32 v181, s8, v181
	v_mul_f32_e32 v182, s8, v182
	v_mul_f32_e32 v183, s8, v183
	v_mul_f32_e32 v184, s8, v184
	v_fmac_f32_e32 v148, v62, v181
	v_fmac_f32_e32 v149, v58, v182
	v_fmac_f32_e32 v150, v54, v183
	v_fmac_f32_e32 v151, v50, v184
	global_store_dword v[136:137], v148, off
	global_store_dword v[136:137], v149, off offset:64
	global_store_dword v[136:137], v150, off offset:128
	global_store_dword v[136:137], v151, off offset:192
	v_add_u32_e32 v180, 0x23, v123
	v_min_i32_e32 v180, 0x8000, v180
	v_xor_b32_e32 v180, v180, v114
	v_cmp_gt_u32_e32 vcc, s10, v180
	s_nop 1
	v_cndmask_b32_e32 v181, v116, v115, vcc
	v_cndmask_b32_e32 v182, v118, v117, vcc
	v_cndmask_b32_e32 v183, v120, v119, vcc
	v_cndmask_b32_e32 v184, v121, v122, vcc
	v_mul_f32_e32 v181, s8, v181
	v_mul_f32_e32 v182, s8, v182
	v_mul_f32_e32 v183, s8, v183
	v_mul_f32_e32 v184, s8, v184
	v_fmac_f32_e32 v152, v63, v181
	v_fmac_f32_e32 v153, v59, v182
	v_fmac_f32_e32 v154, v55, v183
	v_fmac_f32_e32 v155, v51, v184
	global_store_dword v[138:139], v152, off
	global_store_dword v[138:139], v153, off offset:64
	global_store_dword v[138:139], v154, off offset:128
	global_store_dword v[138:139], v155, off offset:192
	v_add_u32_e32 v180, 0x40, v123
	v_cmp_gt_i32_e32 vcc, s77, v180
	v_add_u32_e32 v181, 0xffff8040, v123
	s_nop 1
	v_cndmask_b32_e32 v132, v181, v180, vcc
	v_cndmask_b32_e32 v182, v188, v186, vcc
	v_cndmask_b32_e32 v183, v189, v187, vcc
	v_mad_u64_u32 v[132:133], vcc, v132, v185, v[182:183]
	global_load_dword v140, v[132:133], off
	global_load_dword v141, v[132:133], off offset:64
	global_load_dword v142, v[132:133], off offset:128
	global_load_dword v143, v[132:133], off offset:192
	v_add_u32_e32 v180, 0x41, v123
	v_cmp_gt_i32_e32 vcc, s77, v180
	v_add_u32_e32 v181, 0xffff8041, v123
	s_nop 1
	v_cndmask_b32_e32 v134, v181, v180, vcc
	v_cndmask_b32_e32 v182, v188, v186, vcc
	v_cndmask_b32_e32 v183, v189, v187, vcc
	v_mad_u64_u32 v[134:135], vcc, v134, v185, v[182:183]
	global_load_dword v144, v[134:135], off
	global_load_dword v145, v[134:135], off offset:64
	global_load_dword v146, v[134:135], off offset:128
	global_load_dword v147, v[134:135], off offset:192
	v_add_u32_e32 v180, 0x42, v123
	v_cmp_gt_i32_e32 vcc, s77, v180
	v_add_u32_e32 v181, 0xffff8042, v123
	s_nop 1
	v_cndmask_b32_e32 v136, v181, v180, vcc
	v_cndmask_b32_e32 v182, v188, v186, vcc
	v_cndmask_b32_e32 v183, v189, v187, vcc
	v_mad_u64_u32 v[136:137], vcc, v136, v185, v[182:183]
	global_load_dword v148, v[136:137], off
	global_load_dword v149, v[136:137], off offset:64
	global_load_dword v150, v[136:137], off offset:128
	global_load_dword v151, v[136:137], off offset:192
	v_add_u32_e32 v180, 0x43, v123
	v_cmp_gt_i32_e32 vcc, s77, v180
	v_add_u32_e32 v181, 0xffff8043, v123
	s_nop 1
	v_cndmask_b32_e32 v138, v181, v180, vcc
	v_cndmask_b32_e32 v182, v188, v186, vcc
	v_cndmask_b32_e32 v183, v189, v187, vcc
	v_mad_u64_u32 v[138:139], vcc, v138, v185, v[182:183]
	global_load_dword v152, v[138:139], off
	global_load_dword v153, v[138:139], off offset:64
	global_load_dword v154, v[138:139], off offset:128
	global_load_dword v155, v[138:139], off offset:192
	s_waitcnt vmcnt(31)
; __device__ __forceinline__ void phase_gemm_res(const Params& p, int L, const u16* A, int K, const u16* Bt, int gidx, float factor, char* lds) {
;     ...
; #pragma unroll
;           for (int j = 0; j < 4; ++j) {
;             const int row = m0 + wm * 96 + (2 * mp + u) * 16 + quad * 4 + j;
;             float* xr = xrow(p, row) + n0 + wn * 64 + l15;
;             const bool lo = (row < TL ? (row >> 13) : 4) == clo;
;             float gv[4];
; #pragma unroll
;             for (int ni = 0; ni < 4; ++ni) gv[ni] = lo ? g0[ni] : g1[ni];
; #pragma unroll
;             for (int ni = 0; ni < 4; ++ni) xr[ni * 16] = xv[u][j][ni] + factor * gv[ni] * acc[2 * mp + u][ni][j];
	v_add_u32_e32 v180, 0x30, v123
	v_min_i32_e32 v180, 0x8000, v180
	v_xor_b32_e32 v180, v180, v114
	v_cmp_gt_u32_e32 vcc, s10, v180
	s_nop 1
	v_cndmask_b32_e32 v181, v116, v115, vcc
	v_cndmask_b32_e32 v182, v118, v117, vcc
	v_cndmask_b32_e32 v183, v120, v119, vcc
	v_cndmask_b32_e32 v184, v121, v122, vcc
	v_mul_f32_e32 v181, s8, v181
	v_mul_f32_e32 v182, s8, v182
	v_mul_f32_e32 v183, s8, v183
	v_mul_f32_e32 v184, s8, v184
	v_fmac_f32_e32 v164, v36, v181
	v_fmac_f32_e32 v165, v32, v182
	v_fmac_f32_e32 v166, v40, v183
	v_fmac_f32_e32 v167, v44, v184
	global_store_dword v[156:157], v164, off
	global_store_dword v[156:157], v165, off offset:64
	global_store_dword v[156:157], v166, off offset:128
	global_store_dword v[156:157], v167, off offset:192
	v_add_u32_e32 v180, 0x31, v123
	v_min_i32_e32 v180, 0x8000, v180
	v_xor_b32_e32 v180, v180, v114
	v_cmp_gt_u32_e32 vcc, s10, v180
	s_nop 1
	v_cndmask_b32_e32 v181, v116, v115, vcc
	v_cndmask_b32_e32 v182, v118, v117, vcc
	v_cndmask_b32_e32 v183, v120, v119, vcc
	v_cndmask_b32_e32 v184, v121, v122, vcc
	v_mul_f32_e32 v181, s8, v181
	v_mul_f32_e32 v182, s8, v182
	v_mul_f32_e32 v183, s8, v183
	v_mul_f32_e32 v184, s8, v184
	v_fmac_f32_e32 v168, v37, v181
	v_fmac_f32_e32 v169, v33, v182
	v_fmac_f32_e32 v170, v41, v183
	v_fmac_f32_e32 v171, v45, v184
	global_store_dword v[158:159], v168, off
	global_store_dword v[158:159], v169, off offset:64
	global_store_dword v[158:159], v170, off offset:128
	global_store_dword v[158:159], v171, off offset:192
	v_add_u32_e32 v180, 0x32, v123
	v_min_i32_e32 v180, 0x8000, v180
	v_xor_b32_e32 v180, v180, v114
	v_cmp_gt_u32_e32 vcc, s10, v180
	s_nop 1
	v_cndmask_b32_e32 v181, v116, v115, vcc
	v_cndmask_b32_e32 v182, v118, v117, vcc
	v_cndmask_b32_e32 v183, v120, v119, vcc
	v_cndmask_b32_e32 v184, v121, v122, vcc
	v_mul_f32_e32 v181, s8, v181
	v_mul_f32_e32 v182, s8, v182
	v_mul_f32_e32 v183, s8, v183
	v_mul_f32_e32 v184, s8, v184
	v_fmac_f32_e32 v172, v38, v181
	v_fmac_f32_e32 v173, v34, v182
	v_fmac_f32_e32 v174, v42, v183
	v_fmac_f32_e32 v175, v46, v184
	global_store_dword v[160:161], v172, off
	global_store_dword v[160:161], v173, off offset:64
	global_store_dword v[160:161], v174, off offset:128
	global_store_dword v[160:161], v175, off offset:192
	v_add_u32_e32 v180, 0x33, v123
	v_min_i32_e32 v180, 0x8000, v180
	v_xor_b32_e32 v180, v180, v114
	v_cmp_gt_u32_e32 vcc, s10, v180
	s_nop 1
	v_cndmask_b32_e32 v181, v116, v115, vcc
	v_cndmask_b32_e32 v182, v118, v117, vcc
	v_cndmask_b32_e32 v183, v120, v119, vcc
	v_cndmask_b32_e32 v184, v121, v122, vcc
	v_mul_f32_e32 v181, s8, v181
	v_mul_f32_e32 v182, s8, v182
	v_mul_f32_e32 v183, s8, v183
	v_mul_f32_e32 v184, s8, v184
	v_fmac_f32_e32 v176, v39, v181
	v_fmac_f32_e32 v177, v35, v182
	v_fmac_f32_e32 v178, v43, v183
	v_fmac_f32_e32 v179, v47, v184
	global_store_dword v[162:163], v176, off
	global_store_dword v[162:163], v177, off offset:64
	global_store_dword v[162:163], v178, off offset:128
	global_store_dword v[162:163], v179, off offset:192
	v_add_u32_e32 v180, 0x50, v123
	v_cmp_gt_i32_e32 vcc, s77, v180
	v_add_u32_e32 v181, 0xffff8050, v123
	s_nop 1
	v_cndmask_b32_e32 v156, v181, v180, vcc
	v_cndmask_b32_e32 v182, v188, v186, vcc
	v_cndmask_b32_e32 v183, v189, v187, vcc
	v_mad_u64_u32 v[156:157], vcc, v156, v185, v[182:183]
	global_load_dword v164, v[156:157], off
	global_load_dword v165, v[156:157], off offset:64
	global_load_dword v166, v[156:157], off offset:128
	global_load_dword v167, v[156:157], off offset:192
	v_add_u32_e32 v180, 0x51, v123
	v_cmp_gt_i32_e32 vcc, s77, v180
	v_add_u32_e32 v181, 0xffff8051, v123
	s_nop 1
	v_cndmask_b32_e32 v158, v181, v180, vcc
	v_cndmask_b32_e32 v182, v188, v186, vcc
	v_cndmask_b32_e32 v183, v189, v187, vcc
	v_mad_u64_u32 v[158:159], vcc, v158, v185, v[182:183]
	global_load_dword v168, v[158:159], off
	global_load_dword v169, v[158:159], off offset:64
	global_load_dword v170, v[158:159], off offset:128
	global_load_dword v171, v[158:159], off offset:192
	v_add_u32_e32 v180, 0x52, v123
	v_cmp_gt_i32_e32 vcc, s77, v180
	v_add_u32_e32 v181, 0xffff8052, v123
	s_nop 1
	v_cndmask_b32_e32 v160, v181, v180, vcc
	v_cndmask_b32_e32 v182, v188, v186, vcc
	v_cndmask_b32_e32 v183, v189, v187, vcc
	v_mad_u64_u32 v[160:161], vcc, v160, v185, v[182:183]
	global_load_dword v172, v[160:161], off
	global_load_dword v173, v[160:161], off offset:64
	global_load_dword v174, v[160:161], off offset:128
	global_load_dword v175, v[160:161], off offset:192
	v_add_u32_e32 v180, 0x53, v123
	v_cmp_gt_i32_e32 vcc, s77, v180
	v_add_u32_e32 v181, 0xffff8053, v123
	s_nop 1
	v_cndmask_b32_e32 v162, v181, v180, vcc
	v_cndmask_b32_e32 v182, v188, v186, vcc
	v_cndmask_b32_e32 v183, v189, v187, vcc
	v_mad_u64_u32 v[162:163], vcc, v162, v185, v[182:183]
	global_load_dword v176, v[162:163], off
	global_load_dword v177, v[162:163], off offset:64
	global_load_dword v178, v[162:163], off offset:128
	global_load_dword v179, v[162:163], off offset:192
	s_waitcnt vmcnt(31)
; __device__ __forceinline__ void phase_gemm_res(const Params& p, int L, const u16* A, int K, const u16* Bt, int gidx, float factor, char* lds) {
;     ...
; #pragma unroll
;           for (int j = 0; j < 4; ++j) {
;             const int row = m0 + wm * 96 + (2 * mp + u) * 16 + quad * 4 + j;
;             float* xr = xrow(p, row) + n0 + wn * 64 + l15;
;             const bool lo = (row < TL ? (row >> 13) : 4) == clo;
;             float gv[4];
; #pragma unroll
;             for (int ni = 0; ni < 4; ++ni) gv[ni] = lo ? g0[ni] : g1[ni];
; #pragma unroll
;             for (int ni = 0; ni < 4; ++ni) xr[ni * 16] = xv[u][j][ni] + factor * gv[ni] * acc[2 * mp + u][ni][j];
;           }
;       }
;     });
	v_add_u32_e32 v180, 0x40, v123
	v_min_i32_e32 v180, 0x8000, v180
	v_xor_b32_e32 v180, v180, v114
	v_cmp_gt_u32_e32 vcc, s10, v180
	s_nop 1
	v_cndmask_b32_e32 v181, v116, v115, vcc
	v_cndmask_b32_e32 v182, v118, v117, vcc
	v_cndmask_b32_e32 v183, v120, v119, vcc
	v_cndmask_b32_e32 v184, v121, v122, vcc
	v_mul_f32_e32 v181, s8, v181
	v_mul_f32_e32 v182, s8, v182
	v_mul_f32_e32 v183, s8, v183
	v_mul_f32_e32 v184, s8, v184
	v_fmac_f32_e32 v140, v16, v181
	v_fmac_f32_e32 v141, v20, v182
	v_fmac_f32_e32 v142, v24, v183
	v_fmac_f32_e32 v143, v28, v184
	global_store_dword v[132:133], v140, off
	global_store_dword v[132:133], v141, off offset:64
	global_store_dword v[132:133], v142, off offset:128
	global_store_dword v[132:133], v143, off offset:192
	v_add_u32_e32 v180, 0x41, v123
	v_min_i32_e32 v180, 0x8000, v180
	v_xor_b32_e32 v180, v180, v114
	v_cmp_gt_u32_e32 vcc, s10, v180
	s_nop 1
	v_cndmask_b32_e32 v181, v116, v115, vcc
	v_cndmask_b32_e32 v182, v118, v117, vcc
	v_cndmask_b32_e32 v183, v120, v119, vcc
	v_cndmask_b32_e32 v184, v121, v122, vcc
	v_mul_f32_e32 v181, s8, v181
	v_mul_f32_e32 v182, s8, v182
	v_mul_f32_e32 v183, s8, v183
	v_mul_f32_e32 v184, s8, v184
	v_fmac_f32_e32 v144, v17, v181
	v_fmac_f32_e32 v145, v21, v182
	v_fmac_f32_e32 v146, v25, v183
	v_fmac_f32_e32 v147, v29, v184
	global_store_dword v[134:135], v144, off
	global_store_dword v[134:135], v145, off offset:64
	global_store_dword v[134:135], v146, off offset:128
	global_store_dword v[134:135], v147, off offset:192
	v_add_u32_e32 v180, 0x42, v123
	v_min_i32_e32 v180, 0x8000, v180
	v_xor_b32_e32 v180, v180, v114
	v_cmp_gt_u32_e32 vcc, s10, v180
	s_nop 1
	v_cndmask_b32_e32 v181, v116, v115, vcc
	v_cndmask_b32_e32 v182, v118, v117, vcc
	v_cndmask_b32_e32 v183, v120, v119, vcc
	v_cndmask_b32_e32 v184, v121, v122, vcc
	v_mul_f32_e32 v181, s8, v181
	v_mul_f32_e32 v182, s8, v182
	v_mul_f32_e32 v183, s8, v183
	v_mul_f32_e32 v184, s8, v184
	v_fmac_f32_e32 v148, v18, v181
	v_fmac_f32_e32 v149, v22, v182
	v_fmac_f32_e32 v150, v26, v183
	v_fmac_f32_e32 v151, v30, v184
	global_store_dword v[136:137], v148, off
	global_store_dword v[136:137], v149, off offset:64
	global_store_dword v[136:137], v150, off offset:128
	global_store_dword v[136:137], v151, off offset:192
	v_add_u32_e32 v180, 0x43, v123
	v_min_i32_e32 v180, 0x8000, v180
	v_xor_b32_e32 v180, v180, v114
	v_cmp_gt_u32_e32 vcc, s10, v180
	s_nop 1
	v_cndmask_b32_e32 v181, v116, v115, vcc
	v_cndmask_b32_e32 v182, v118, v117, vcc
	v_cndmask_b32_e32 v183, v120, v119, vcc
	v_cndmask_b32_e32 v184, v121, v122, vcc
	v_mul_f32_e32 v181, s8, v181
	v_mul_f32_e32 v182, s8, v182
	v_mul_f32_e32 v183, s8, v183
	v_mul_f32_e32 v184, s8, v184
	v_fmac_f32_e32 v152, v19, v181
	v_fmac_f32_e32 v153, v23, v182
	v_fmac_f32_e32 v154, v27, v183
	v_fmac_f32_e32 v155, v31, v184
	global_store_dword v[138:139], v152, off
	global_store_dword v[138:139], v153, off offset:64
	global_store_dword v[138:139], v154, off offset:128
	global_store_dword v[138:139], v155, off offset:192
	v_readlane_b32 s13, v253, 33
	v_readlane_b32 s14, v255, 25
	v_readlane_b32 s15, v255, 26
	v_readlane_b32 s16, v253, 36
	v_readlane_b32 s17, v253, 37
	v_readlane_b32 s18, v253, 38
	v_readlane_b32 s19, v253, 39
	v_readlane_b32 s20, v253, 40
	v_readlane_b32 s21, v253, 41
	v_readlane_b32 s22, v253, 42
	v_readlane_b32 s23, v253, 43
	v_readlane_b32 s24, v253, 44
	v_readlane_b32 s25, v253, 45
	s_waitcnt vmcnt(16)
	v_add_u32_e32 v180, 0x50, v123
	v_min_i32_e32 v180, 0x8000, v180
	v_xor_b32_e32 v180, v180, v114
	v_cmp_gt_u32_e32 vcc, s10, v180
	s_nop 1
	v_cndmask_b32_e32 v181, v116, v115, vcc
	v_cndmask_b32_e32 v182, v118, v117, vcc
	v_cndmask_b32_e32 v183, v120, v119, vcc
	v_cndmask_b32_e32 v184, v121, v122, vcc
	v_mul_f32_e32 v181, s8, v181
	v_mul_f32_e32 v182, s8, v182
	v_mul_f32_e32 v183, s8, v183
	v_mul_f32_e32 v184, s8, v184
	v_fmac_f32_e32 v164, v0, v181
	v_fmac_f32_e32 v165, v4, v182
	v_fmac_f32_e32 v166, v8, v183
	v_fmac_f32_e32 v167, v12, v184
	global_store_dword v[156:157], v164, off
	global_store_dword v[156:157], v165, off offset:64
	global_store_dword v[156:157], v166, off offset:128
	global_store_dword v[156:157], v167, off offset:192
	v_add_u32_e32 v180, 0x51, v123
	v_min_i32_e32 v180, 0x8000, v180
	v_xor_b32_e32 v180, v180, v114
	v_cmp_gt_u32_e32 vcc, s10, v180
	s_nop 1
	v_cndmask_b32_e32 v181, v116, v115, vcc
	v_cndmask_b32_e32 v182, v118, v117, vcc
	v_cndmask_b32_e32 v183, v120, v119, vcc
	v_cndmask_b32_e32 v184, v121, v122, vcc
	v_mul_f32_e32 v181, s8, v181
	v_mul_f32_e32 v182, s8, v182
	v_mul_f32_e32 v183, s8, v183
	v_mul_f32_e32 v184, s8, v184
	v_fmac_f32_e32 v168, v1, v181
	v_fmac_f32_e32 v169, v5, v182
	v_fmac_f32_e32 v170, v9, v183
	v_fmac_f32_e32 v171, v13, v184
	global_store_dword v[158:159], v168, off
	global_store_dword v[158:159], v169, off offset:64
	global_store_dword v[158:159], v170, off offset:128
	global_store_dword v[158:159], v171, off offset:192
	v_add_u32_e32 v180, 0x52, v123
	v_min_i32_e32 v180, 0x8000, v180
	v_xor_b32_e32 v180, v180, v114
	v_cmp_gt_u32_e32 vcc, s10, v180
	s_nop 1
	v_cndmask_b32_e32 v181, v116, v115, vcc
	v_cndmask_b32_e32 v182, v118, v117, vcc
	v_cndmask_b32_e32 v183, v120, v119, vcc
	v_cndmask_b32_e32 v184, v121, v122, vcc
	v_mul_f32_e32 v181, s8, v181
	v_mul_f32_e32 v182, s8, v182
	v_mul_f32_e32 v183, s8, v183
	v_mul_f32_e32 v184, s8, v184
	v_fmac_f32_e32 v172, v2, v181
	v_fmac_f32_e32 v173, v6, v182
	v_fmac_f32_e32 v174, v10, v183
	v_fmac_f32_e32 v175, v14, v184
	global_store_dword v[160:161], v172, off
	global_store_dword v[160:161], v173, off offset:64
	global_store_dword v[160:161], v174, off offset:128
	global_store_dword v[160:161], v175, off offset:192
	v_add_u32_e32 v180, 0x53, v123
	v_min_i32_e32 v180, 0x8000, v180
	v_xor_b32_e32 v180, v180, v114
	v_cmp_gt_u32_e32 vcc, s10, v180
	s_nop 1
	v_cndmask_b32_e32 v181, v116, v115, vcc
	v_cndmask_b32_e32 v182, v118, v117, vcc
	v_cndmask_b32_e32 v183, v120, v119, vcc
	v_cndmask_b32_e32 v184, v121, v122, vcc
	v_mul_f32_e32 v181, s8, v181
	v_mul_f32_e32 v182, s8, v182
	v_mul_f32_e32 v183, s8, v183
	v_mul_f32_e32 v184, s8, v184
	v_fmac_f32_e32 v176, v3, v181
	v_fmac_f32_e32 v177, v7, v182
	v_fmac_f32_e32 v178, v11, v183
	v_fmac_f32_e32 v179, v15, v184
	global_store_dword v[162:163], v176, off
	global_store_dword v[162:163], v177, off offset:64
	global_store_dword v[162:163], v178, off offset:128
	global_store_dword v[162:163], v179, off offset:192
	v_mov_b32_e32 v124, s59
	v_mov_b32_e32 v125, s27
	v_mov_b32_e32 v126, s58
	v_mov_b32_e32 v127, s26
	s_movk_i32 s12, 0x7ffd
	s_add_i32 s63, s63, s33
	s_cmpk_gt_i32 s63, 0x2bf
	s_cbranch_scc1 .LBB0_1763
